# attn_combine executed only by the half of the grid without HGRN items (two passes each), G=256
# speedup vs baseline: 1.0742x; 1.0035x over previous
; __device__ __forceinline__ unsigned cvt_pk_bf16(float lo, float hi) { f32x2_t v = {lo, hi}; bf2_t r = __builtin_convertvector(v, bf2_t); return __builtin_bit_cast(unsigned, r); }
; __device__ __forceinline__ float bflo(unsigned u) { return __uint_as_float(u << 16); }
; __device__ __forceinline__ float bfhi(unsigned u) { return __uint_as_float(u & 0xffff0000u); }
;     __device__ __forceinline__ bf16_t* bfp(size_t off) const { return (bf16_t*)(ws + off); }
;     __device__ __forceinline__ float* fp(size_t off) const { return (float*)(ws + off); }
; __device__ __forceinline__ void attn_combine(const Ctx& C) {
;     const bf16_t* pd = C.bfp(OFF_PROJD); const float* lse = C.fp(OFF_LSE); bf16_t* yd = C.bfp(OFF_YD);
;     for (int idx = C.bid * NTHR + C.tid; idx < M_TOK * 32; idx += C.G * NTHR) {
;         const int tok = idx >> 5, j = (idx >> 3) & 3, c8 = idx & 7;
;         const float l0 = lse[((size_t)0 * M_TOK + tok) * 4 + j], l1 = lse[((size_t)1 * M_TOK + tok) * 4 + j], l2 = lse[((size_t)2 * M_TOK + tok) * 4 + j];
;         const float mx = fmaxf(l0, fmaxf(l1, l2)); float w0 = __expf(l0 - mx), w1 = __expf(l1 - mx), w2 = __expf(l2 - mx); const float inv = 1.0f / (w0 + w1 + w2); w0 *= inv; w1 *= inv; w2 *= inv;
;         const bf16_t* row = pd + (size_t)tok * 2304 + j * 64 + c8 * 8;
;         const u32x4 o0 = *(const u32x4*)row, o1 = *(const u32x4*)(row + 256), o2 = *(const u32x4*)(row + 512);
;         u32x4 o;
;         o.x = cvt_pk_bf16(w0 * bflo(o0.x) + w1 * bflo(o1.x) + w2 * bflo(o2.x), w0 * bfhi(o0.x) + w1 * bfhi(o1.x) + w2 * bfhi(o2.x));
;         o.y = cvt_pk_bf16(w0 * bflo(o0.y) + w1 * bflo(o1.y) + w2 * bflo(o2.y), w0 * bfhi(o0.y) + w1 * bfhi(o1.y) + w2 * bfhi(o2.y));
;         o.z = cvt_pk_bf16(w0 * bflo(o0.z) + w1 * bflo(o1.z) + w2 * bflo(o2.z), w0 * bfhi(o0.z) + w1 * bfhi(o1.z) + w2 * bfhi(o2.z));
;         o.w = cvt_pk_bf16(w0 * bflo(o0.w) + w1 * bflo(o1.w) + w2 * bflo(o2.w), w0 * bfhi(o0.w) + w1 * bfhi(o1.w) + w2 * bfhi(o2.w));
;         *(u32x4*)(yd + (size_t)tok * 256 + j * 64 + c8 * 8) = o;
.LBB0_751:
	s_cmpk_lg_i32 s26, 0x100
	s_cbranch_scc1 .Lmy_cmb_generic
	s_cmpk_lt_u32 s90, 0x80
	s_cbranch_scc1 .Lmy_cmb_done
	v_readlane_b32 s100, v253, 25
	s_mov_b32 s101, 0
.Lmy_cmb_pass:
	s_add_u32 s4, s24, 0xe000000
	s_addc_u32 s5, s25, 0
	s_add_u32 s6, s24, 0x1a000000
	s_addc_u32 s7, s25, 0
	s_add_u32 s8, s24, 0x1b180000
	s_addc_u32 s9, s25, 0
	v_add_u32_e32 v0, s100, v224
	v_lshrrev_b32_e32 v1, 5, v0
	v_bfe_u32 v2, v0, 3, 2
	v_and_b32_e32 v3, 7, v0
	v_lshlrev_b32_e32 v4, 7, v2
	v_lshl_add_u32 v4, v3, 4, v4
	v_lshlrev_b32_e32 v5, 2, v2
	v_lshl_add_u32 v10, v1, 4, v5
	v_add_u32_e32 v11, 0x80000, v10
	v_add_u32_e32 v12, 0x100000, v10
	s_movk_i32 s0, 0x1200
	v_mad_u32_u24 v13, v1, s0, v4
	v_lshl_add_u32 v14, v1, 9, v4
	global_load_dword v164, v10, s[6:7]
	global_load_dword v165, v11, s[6:7]
	global_load_dword v166, v12, s[6:7]
	s_add_u32 s6, s6, 0x10000
	s_addc_u32 s7, s7, 0
	global_load_dword v167, v10, s[6:7]
	global_load_dword v168, v11, s[6:7]
	global_load_dword v169, v12, s[6:7]
	s_add_u32 s6, s6, 0x10000
	s_addc_u32 s7, s7, 0
	global_load_dword v170, v10, s[6:7]
	global_load_dword v171, v11, s[6:7]
	global_load_dword v172, v12, s[6:7]
	s_add_u32 s6, s6, 0x10000
	s_addc_u32 s7, s7, 0
	global_load_dword v173, v10, s[6:7]
	global_load_dword v174, v11, s[6:7]
	global_load_dword v175, v12, s[6:7]
	s_add_u32 s6, s6, 0x10000
	s_addc_u32 s7, s7, 0
	global_load_dword v176, v10, s[6:7]
	global_load_dword v177, v11, s[6:7]
	global_load_dword v178, v12, s[6:7]
	s_add_u32 s6, s6, 0x10000
	s_addc_u32 s7, s7, 0
	global_load_dword v179, v10, s[6:7]
	global_load_dword v180, v11, s[6:7]
	global_load_dword v181, v12, s[6:7]
	s_add_u32 s6, s6, 0x10000
	s_addc_u32 s7, s7, 0
	global_load_dword v188, v10, s[6:7]
	global_load_dword v189, v11, s[6:7]
	global_load_dword v190, v12, s[6:7]
	s_add_u32 s6, s6, 0x10000
	s_addc_u32 s7, s7, 0
	global_load_dword v191, v10, s[6:7]
	global_load_dword v192, v11, s[6:7]
	global_load_dword v193, v12, s[6:7]
	global_load_dwordx4 v[68:71], v13, s[4:5]
	global_load_dwordx4 v[72:75], v13, s[4:5] offset:512
	global_load_dwordx4 v[76:79], v13, s[4:5] offset:1024
	s_add_u32 s4, s4, 0x1200000
	s_addc_u32 s5, s5, 0
	global_load_dwordx4 v[80:83], v13, s[4:5]
	global_load_dwordx4 v[84:87], v13, s[4:5] offset:512
	global_load_dwordx4 v[88:91], v13, s[4:5] offset:1024
	s_add_u32 s4, s4, 0x1200000
	s_addc_u32 s5, s5, 0
	global_load_dwordx4 v[92:95], v13, s[4:5]
	global_load_dwordx4 v[96:99], v13, s[4:5] offset:512
	global_load_dwordx4 v[100:103], v13, s[4:5] offset:1024
	s_add_u32 s4, s4, 0x1200000
	s_addc_u32 s5, s5, 0
	global_load_dwordx4 v[104:107], v13, s[4:5]
	global_load_dwordx4 v[108:111], v13, s[4:5] offset:512
	global_load_dwordx4 v[112:115], v13, s[4:5] offset:1024
	s_add_u32 s4, s4, 0x1200000
	s_addc_u32 s5, s5, 0
	global_load_dwordx4 v[116:119], v13, s[4:5]
	global_load_dwordx4 v[120:123], v13, s[4:5] offset:512
	global_load_dwordx4 v[124:127], v13, s[4:5] offset:1024
	s_add_u32 s4, s4, 0x1200000
	s_addc_u32 s5, s5, 0
	global_load_dwordx4 v[128:131], v13, s[4:5]
	global_load_dwordx4 v[132:135], v13, s[4:5] offset:512
	global_load_dwordx4 v[136:139], v13, s[4:5] offset:1024
	s_add_u32 s4, s4, 0x1200000
	s_addc_u32 s5, s5, 0
	global_load_dwordx4 v[140:143], v13, s[4:5]
	global_load_dwordx4 v[144:147], v13, s[4:5] offset:512
	global_load_dwordx4 v[148:151], v13, s[4:5] offset:1024
	s_add_u32 s4, s4, 0x1200000
	s_addc_u32 s5, s5, 0
	global_load_dwordx4 v[152:155], v13, s[4:5]
	global_load_dwordx4 v[156:159], v13, s[4:5] offset:512
	global_load_dwordx4 v[160:163], v13, s[4:5] offset:1024
	s_waitcnt vmcnt(45)
	v_max3_f32 v20, v164, v165, v166
	v_sub_f32_e32 v21, v164, v20
	v_sub_f32_e32 v22, v165, v20
	v_sub_f32_e32 v23, v166, v20
	v_mul_f32_e32 v21, 0x3fb8aa3b, v21
	v_mul_f32_e32 v22, 0x3fb8aa3b, v22
	v_mul_f32_e32 v23, 0x3fb8aa3b, v23
	v_exp_f32_e32 v21, v21
	v_exp_f32_e32 v22, v22
	v_exp_f32_e32 v23, v23
	s_nop 0
	v_add_f32_e32 v24, v21, v22
	v_add_f32_e32 v24, v23, v24
	v_rcp_f32_e32 v24, v24
	s_nop 0
	v_mul_f32_e32 v21, v21, v24
	v_mul_f32_e32 v22, v22, v24
	v_mul_f32_e32 v23, v23, v24
	s_waitcnt vmcnt(21)
	v_lshlrev_b32_e32 v25, 16, v68
	v_and_b32_e32 v26, 0xffff0000, v68
	v_lshlrev_b32_e32 v27, 16, v72
	v_and_b32_e32 v28, 0xffff0000, v72
	v_lshlrev_b32_e32 v29, 16, v76
	v_and_b32_e32 v30, 0xffff0000, v76
	v_mul_f32_e32 v31, v21, v25
	v_mul_f32_e32 v32, v22, v28
	v_fmac_f32_e32 v31, v22, v27
	v_fmac_f32_e32 v32, v21, v26
	v_fmac_f32_e32 v31, v23, v29
	v_fmac_f32_e32 v32, v23, v30
	v_cvt_pk_bf16_f32 v68, v31, v32
	v_lshlrev_b32_e32 v25, 16, v69
	v_and_b32_e32 v26, 0xffff0000, v69
	v_lshlrev_b32_e32 v27, 16, v73
	v_and_b32_e32 v28, 0xffff0000, v73
	v_lshlrev_b32_e32 v29, 16, v77
	v_and_b32_e32 v30, 0xffff0000, v77
	v_mul_f32_e32 v31, v21, v25
	v_mul_f32_e32 v32, v22, v28
	v_fmac_f32_e32 v31, v22, v27
	v_fmac_f32_e32 v32, v21, v26
	v_fmac_f32_e32 v31, v23, v29
	v_fmac_f32_e32 v32, v23, v30
	v_cvt_pk_bf16_f32 v69, v31, v32
	v_lshlrev_b32_e32 v25, 16, v70
	v_and_b32_e32 v26, 0xffff0000, v70
	v_lshlrev_b32_e32 v27, 16, v74
	v_and_b32_e32 v28, 0xffff0000, v74
	v_lshlrev_b32_e32 v29, 16, v78
	v_and_b32_e32 v30, 0xffff0000, v78
	v_mul_f32_e32 v31, v21, v25
	v_mul_f32_e32 v32, v22, v28
	v_fmac_f32_e32 v31, v22, v27
	v_fmac_f32_e32 v32, v21, v26
	v_fmac_f32_e32 v31, v23, v29
	v_fmac_f32_e32 v32, v23, v30
	v_cvt_pk_bf16_f32 v70, v31, v32
	v_lshlrev_b32_e32 v25, 16, v71
	v_and_b32_e32 v26, 0xffff0000, v71
	v_lshlrev_b32_e32 v27, 16, v75
	v_and_b32_e32 v28, 0xffff0000, v75
	v_lshlrev_b32_e32 v29, 16, v79
	v_and_b32_e32 v30, 0xffff0000, v79
	v_mul_f32_e32 v31, v21, v25
	v_mul_f32_e32 v32, v22, v28
	v_fmac_f32_e32 v31, v22, v27
	v_fmac_f32_e32 v32, v21, v26
	v_fmac_f32_e32 v31, v23, v29
	v_fmac_f32_e32 v32, v23, v30
	v_cvt_pk_bf16_f32 v71, v31, v32
	global_store_dwordx4 v14, v[68:71], s[8:9]
	s_add_u32 s8, s8, 0x200000
	s_addc_u32 s9, s9, 0
	v_max3_f32 v20, v167, v168, v169
	v_sub_f32_e32 v21, v167, v20
	v_sub_f32_e32 v22, v168, v20
	v_sub_f32_e32 v23, v169, v20
	v_mul_f32_e32 v21, 0x3fb8aa3b, v21
	v_mul_f32_e32 v22, 0x3fb8aa3b, v22
	v_mul_f32_e32 v23, 0x3fb8aa3b, v23
	v_exp_f32_e32 v21, v21
	v_exp_f32_e32 v22, v22
	v_exp_f32_e32 v23, v23
	s_nop 0
	v_add_f32_e32 v24, v21, v22
	v_add_f32_e32 v24, v23, v24
	v_rcp_f32_e32 v24, v24
	s_nop 0
	v_mul_f32_e32 v21, v21, v24
	v_mul_f32_e32 v22, v22, v24
	v_mul_f32_e32 v23, v23, v24
	s_waitcnt vmcnt(19)
; __device__ __forceinline__ unsigned cvt_pk_bf16(float lo, float hi) { f32x2_t v = {lo, hi}; bf2_t r = __builtin_convertvector(v, bf2_t); return __builtin_bit_cast(unsigned, r); }
; __device__ __forceinline__ float bflo(unsigned u) { return __uint_as_float(u << 16); }
; __device__ __forceinline__ float bfhi(unsigned u) { return __uint_as_float(u & 0xffff0000u); }
; __device__ __forceinline__ void attn_combine(const Ctx& C) {
;     ...
;         const float l0 = lse[((size_t)0 * M_TOK + tok) * 4 + j], l1 = lse[((size_t)1 * M_TOK + tok) * 4 + j], l2 = lse[((size_t)2 * M_TOK + tok) * 4 + j];
;         const float mx = fmaxf(l0, fmaxf(l1, l2)); float w0 = __expf(l0 - mx), w1 = __expf(l1 - mx), w2 = __expf(l2 - mx); const float inv = 1.0f / (w0 + w1 + w2); w0 *= inv; w1 *= inv; w2 *= inv;
;         const bf16_t* row = pd + (size_t)tok * 2304 + j * 64 + c8 * 8;
;         const u32x4 o0 = *(const u32x4*)row, o1 = *(const u32x4*)(row + 256), o2 = *(const u32x4*)(row + 512);
;         u32x4 o;
;         o.x = cvt_pk_bf16(w0 * bflo(o0.x) + w1 * bflo(o1.x) + w2 * bflo(o2.x), w0 * bfhi(o0.x) + w1 * bfhi(o1.x) + w2 * bfhi(o2.x));
;         o.y = cvt_pk_bf16(w0 * bflo(o0.y) + w1 * bflo(o1.y) + w2 * bflo(o2.y), w0 * bfhi(o0.y) + w1 * bfhi(o1.y) + w2 * bfhi(o2.y));
;         o.z = cvt_pk_bf16(w0 * bflo(o0.z) + w1 * bflo(o1.z) + w2 * bflo(o2.z), w0 * bfhi(o0.z) + w1 * bfhi(o1.z) + w2 * bfhi(o2.z));
;         o.w = cvt_pk_bf16(w0 * bflo(o0.w) + w1 * bflo(o1.w) + w2 * bflo(o2.w), w0 * bfhi(o0.w) + w1 * bfhi(o1.w) + w2 * bfhi(o2.w));
;         *(u32x4*)(yd + (size_t)tok * 256 + j * 64 + c8 * 8) = o;
	v_lshlrev_b32_e32 v25, 16, v80
	v_and_b32_e32 v26, 0xffff0000, v80
	v_lshlrev_b32_e32 v27, 16, v84
	v_and_b32_e32 v28, 0xffff0000, v84
	v_lshlrev_b32_e32 v29, 16, v88
	v_and_b32_e32 v30, 0xffff0000, v88
	v_mul_f32_e32 v31, v21, v25
	v_mul_f32_e32 v32, v22, v28
	v_fmac_f32_e32 v31, v22, v27
	v_fmac_f32_e32 v32, v21, v26
	v_fmac_f32_e32 v31, v23, v29
	v_fmac_f32_e32 v32, v23, v30
	v_cvt_pk_bf16_f32 v80, v31, v32
	v_lshlrev_b32_e32 v25, 16, v81
	v_and_b32_e32 v26, 0xffff0000, v81
	v_lshlrev_b32_e32 v27, 16, v85
	v_and_b32_e32 v28, 0xffff0000, v85
	v_lshlrev_b32_e32 v29, 16, v89
	v_and_b32_e32 v30, 0xffff0000, v89
	v_mul_f32_e32 v31, v21, v25
	v_mul_f32_e32 v32, v22, v28
	v_fmac_f32_e32 v31, v22, v27
	v_fmac_f32_e32 v32, v21, v26
	v_fmac_f32_e32 v31, v23, v29
	v_fmac_f32_e32 v32, v23, v30
	v_cvt_pk_bf16_f32 v81, v31, v32
	v_lshlrev_b32_e32 v25, 16, v82
	v_and_b32_e32 v26, 0xffff0000, v82
	v_lshlrev_b32_e32 v27, 16, v86
	v_and_b32_e32 v28, 0xffff0000, v86
	v_lshlrev_b32_e32 v29, 16, v90
	v_and_b32_e32 v30, 0xffff0000, v90
	v_mul_f32_e32 v31, v21, v25
	v_mul_f32_e32 v32, v22, v28
	v_fmac_f32_e32 v31, v22, v27
	v_fmac_f32_e32 v32, v21, v26
	v_fmac_f32_e32 v31, v23, v29
	v_fmac_f32_e32 v32, v23, v30
	v_cvt_pk_bf16_f32 v82, v31, v32
	v_lshlrev_b32_e32 v25, 16, v83
	v_and_b32_e32 v26, 0xffff0000, v83
	v_lshlrev_b32_e32 v27, 16, v87
	v_and_b32_e32 v28, 0xffff0000, v87
	v_lshlrev_b32_e32 v29, 16, v91
	v_and_b32_e32 v30, 0xffff0000, v91
	v_mul_f32_e32 v31, v21, v25
	v_mul_f32_e32 v32, v22, v28
	v_fmac_f32_e32 v31, v22, v27
	v_fmac_f32_e32 v32, v21, v26
	v_fmac_f32_e32 v31, v23, v29
	v_fmac_f32_e32 v32, v23, v30
	v_cvt_pk_bf16_f32 v83, v31, v32
	global_store_dwordx4 v14, v[80:83], s[8:9]
	s_add_u32 s8, s8, 0x200000
	s_addc_u32 s9, s9, 0
	v_max3_f32 v20, v170, v171, v172
	v_sub_f32_e32 v21, v170, v20
	v_sub_f32_e32 v22, v171, v20
	v_sub_f32_e32 v23, v172, v20
	v_mul_f32_e32 v21, 0x3fb8aa3b, v21
	v_mul_f32_e32 v22, 0x3fb8aa3b, v22
	v_mul_f32_e32 v23, 0x3fb8aa3b, v23
	v_exp_f32_e32 v21, v21
	v_exp_f32_e32 v22, v22
	v_exp_f32_e32 v23, v23
	s_nop 0
	v_add_f32_e32 v24, v21, v22
	v_add_f32_e32 v24, v23, v24
	v_rcp_f32_e32 v24, v24
	s_nop 0
	v_mul_f32_e32 v21, v21, v24
	v_mul_f32_e32 v22, v22, v24
	v_mul_f32_e32 v23, v23, v24
	s_waitcnt vmcnt(17)
	v_lshlrev_b32_e32 v25, 16, v92
	v_and_b32_e32 v26, 0xffff0000, v92
	v_lshlrev_b32_e32 v27, 16, v96
	v_and_b32_e32 v28, 0xffff0000, v96
	v_lshlrev_b32_e32 v29, 16, v100
	v_and_b32_e32 v30, 0xffff0000, v100
	v_mul_f32_e32 v31, v21, v25
	v_mul_f32_e32 v32, v22, v28
	v_fmac_f32_e32 v31, v22, v27
	v_fmac_f32_e32 v32, v21, v26
	v_fmac_f32_e32 v31, v23, v29
	v_fmac_f32_e32 v32, v23, v30
	v_cvt_pk_bf16_f32 v92, v31, v32
	v_lshlrev_b32_e32 v25, 16, v93
	v_and_b32_e32 v26, 0xffff0000, v93
	v_lshlrev_b32_e32 v27, 16, v97
	v_and_b32_e32 v28, 0xffff0000, v97
	v_lshlrev_b32_e32 v29, 16, v101
	v_and_b32_e32 v30, 0xffff0000, v101
	v_mul_f32_e32 v31, v21, v25
	v_mul_f32_e32 v32, v22, v28
	v_fmac_f32_e32 v31, v22, v27
	v_fmac_f32_e32 v32, v21, v26
	v_fmac_f32_e32 v31, v23, v29
	v_fmac_f32_e32 v32, v23, v30
	v_cvt_pk_bf16_f32 v93, v31, v32
	v_lshlrev_b32_e32 v25, 16, v94
	v_and_b32_e32 v26, 0xffff0000, v94
	v_lshlrev_b32_e32 v27, 16, v98
	v_and_b32_e32 v28, 0xffff0000, v98
	v_lshlrev_b32_e32 v29, 16, v102
	v_and_b32_e32 v30, 0xffff0000, v102
	v_mul_f32_e32 v31, v21, v25
	v_mul_f32_e32 v32, v22, v28
	v_fmac_f32_e32 v31, v22, v27
	v_fmac_f32_e32 v32, v21, v26
	v_fmac_f32_e32 v31, v23, v29
	v_fmac_f32_e32 v32, v23, v30
	v_cvt_pk_bf16_f32 v94, v31, v32
	v_lshlrev_b32_e32 v25, 16, v95
	v_and_b32_e32 v26, 0xffff0000, v95
	v_lshlrev_b32_e32 v27, 16, v99
	v_and_b32_e32 v28, 0xffff0000, v99
	v_lshlrev_b32_e32 v29, 16, v103
	v_and_b32_e32 v30, 0xffff0000, v103
	v_mul_f32_e32 v31, v21, v25
	v_mul_f32_e32 v32, v22, v28
	v_fmac_f32_e32 v31, v22, v27
	v_fmac_f32_e32 v32, v21, v26
	v_fmac_f32_e32 v31, v23, v29
	v_fmac_f32_e32 v32, v23, v30
	v_cvt_pk_bf16_f32 v95, v31, v32
	global_store_dwordx4 v14, v[92:95], s[8:9]
	s_add_u32 s8, s8, 0x200000
	s_addc_u32 s9, s9, 0
	v_max3_f32 v20, v173, v174, v175
	v_sub_f32_e32 v21, v173, v20
	v_sub_f32_e32 v22, v174, v20
	v_sub_f32_e32 v23, v175, v20
	v_mul_f32_e32 v21, 0x3fb8aa3b, v21
	v_mul_f32_e32 v22, 0x3fb8aa3b, v22
	v_mul_f32_e32 v23, 0x3fb8aa3b, v23
	v_exp_f32_e32 v21, v21
	v_exp_f32_e32 v22, v22
	v_exp_f32_e32 v23, v23
	s_nop 0
	v_add_f32_e32 v24, v21, v22
	v_add_f32_e32 v24, v23, v24
	v_rcp_f32_e32 v24, v24
	s_nop 0
	v_mul_f32_e32 v21, v21, v24
	v_mul_f32_e32 v22, v22, v24
	v_mul_f32_e32 v23, v23, v24
	s_waitcnt vmcnt(15)
; __device__ __forceinline__ unsigned cvt_pk_bf16(float lo, float hi) { f32x2_t v = {lo, hi}; bf2_t r = __builtin_convertvector(v, bf2_t); return __builtin_bit_cast(unsigned, r); }
; __device__ __forceinline__ float bflo(unsigned u) { return __uint_as_float(u << 16); }
; __device__ __forceinline__ float bfhi(unsigned u) { return __uint_as_float(u & 0xffff0000u); }
; __device__ __forceinline__ void attn_combine(const Ctx& C) {
;     ...
;         const float l0 = lse[((size_t)0 * M_TOK + tok) * 4 + j], l1 = lse[((size_t)1 * M_TOK + tok) * 4 + j], l2 = lse[((size_t)2 * M_TOK + tok) * 4 + j];
;         const float mx = fmaxf(l0, fmaxf(l1, l2)); float w0 = __expf(l0 - mx), w1 = __expf(l1 - mx), w2 = __expf(l2 - mx); const float inv = 1.0f / (w0 + w1 + w2); w0 *= inv; w1 *= inv; w2 *= inv;
;         const bf16_t* row = pd + (size_t)tok * 2304 + j * 64 + c8 * 8;
;         const u32x4 o0 = *(const u32x4*)row, o1 = *(const u32x4*)(row + 256), o2 = *(const u32x4*)(row + 512);
;         u32x4 o;
;         o.x = cvt_pk_bf16(w0 * bflo(o0.x) + w1 * bflo(o1.x) + w2 * bflo(o2.x), w0 * bfhi(o0.x) + w1 * bfhi(o1.x) + w2 * bfhi(o2.x));
;         o.y = cvt_pk_bf16(w0 * bflo(o0.y) + w1 * bflo(o1.y) + w2 * bflo(o2.y), w0 * bfhi(o0.y) + w1 * bfhi(o1.y) + w2 * bfhi(o2.y));
;         o.z = cvt_pk_bf16(w0 * bflo(o0.z) + w1 * bflo(o1.z) + w2 * bflo(o2.z), w0 * bfhi(o0.z) + w1 * bfhi(o1.z) + w2 * bfhi(o2.z));
;         o.w = cvt_pk_bf16(w0 * bflo(o0.w) + w1 * bflo(o1.w) + w2 * bflo(o2.w), w0 * bfhi(o0.w) + w1 * bfhi(o1.w) + w2 * bfhi(o2.w));
;         *(u32x4*)(yd + (size_t)tok * 256 + j * 64 + c8 * 8) = o;
	v_lshlrev_b32_e32 v25, 16, v104
	v_and_b32_e32 v26, 0xffff0000, v104
	v_lshlrev_b32_e32 v27, 16, v108
	v_and_b32_e32 v28, 0xffff0000, v108
	v_lshlrev_b32_e32 v29, 16, v112
	v_and_b32_e32 v30, 0xffff0000, v112
	v_mul_f32_e32 v31, v21, v25
	v_mul_f32_e32 v32, v22, v28
	v_fmac_f32_e32 v31, v22, v27
	v_fmac_f32_e32 v32, v21, v26
	v_fmac_f32_e32 v31, v23, v29
	v_fmac_f32_e32 v32, v23, v30
	v_cvt_pk_bf16_f32 v104, v31, v32
	v_lshlrev_b32_e32 v25, 16, v105
	v_and_b32_e32 v26, 0xffff0000, v105
	v_lshlrev_b32_e32 v27, 16, v109
	v_and_b32_e32 v28, 0xffff0000, v109
	v_lshlrev_b32_e32 v29, 16, v113
	v_and_b32_e32 v30, 0xffff0000, v113
	v_mul_f32_e32 v31, v21, v25
	v_mul_f32_e32 v32, v22, v28
	v_fmac_f32_e32 v31, v22, v27
	v_fmac_f32_e32 v32, v21, v26
	v_fmac_f32_e32 v31, v23, v29
	v_fmac_f32_e32 v32, v23, v30
	v_cvt_pk_bf16_f32 v105, v31, v32
	v_lshlrev_b32_e32 v25, 16, v106
	v_and_b32_e32 v26, 0xffff0000, v106
	v_lshlrev_b32_e32 v27, 16, v110
	v_and_b32_e32 v28, 0xffff0000, v110
	v_lshlrev_b32_e32 v29, 16, v114
	v_and_b32_e32 v30, 0xffff0000, v114
	v_mul_f32_e32 v31, v21, v25
	v_mul_f32_e32 v32, v22, v28
	v_fmac_f32_e32 v31, v22, v27
	v_fmac_f32_e32 v32, v21, v26
	v_fmac_f32_e32 v31, v23, v29
	v_fmac_f32_e32 v32, v23, v30
	v_cvt_pk_bf16_f32 v106, v31, v32
	v_lshlrev_b32_e32 v25, 16, v107
	v_and_b32_e32 v26, 0xffff0000, v107
	v_lshlrev_b32_e32 v27, 16, v111
	v_and_b32_e32 v28, 0xffff0000, v111
	v_lshlrev_b32_e32 v29, 16, v115
	v_and_b32_e32 v30, 0xffff0000, v115
	v_mul_f32_e32 v31, v21, v25
	v_mul_f32_e32 v32, v22, v28
	v_fmac_f32_e32 v31, v22, v27
	v_fmac_f32_e32 v32, v21, v26
	v_fmac_f32_e32 v31, v23, v29
	v_fmac_f32_e32 v32, v23, v30
	v_cvt_pk_bf16_f32 v107, v31, v32
	global_store_dwordx4 v14, v[104:107], s[8:9]
	s_add_u32 s8, s8, 0x200000
	s_addc_u32 s9, s9, 0
	v_max3_f32 v20, v176, v177, v178
	v_sub_f32_e32 v21, v176, v20
	v_sub_f32_e32 v22, v177, v20
	v_sub_f32_e32 v23, v178, v20
	v_mul_f32_e32 v21, 0x3fb8aa3b, v21
	v_mul_f32_e32 v22, 0x3fb8aa3b, v22
	v_mul_f32_e32 v23, 0x3fb8aa3b, v23
	v_exp_f32_e32 v21, v21
	v_exp_f32_e32 v22, v22
	v_exp_f32_e32 v23, v23
	s_nop 0
	v_add_f32_e32 v24, v21, v22
	v_add_f32_e32 v24, v23, v24
	v_rcp_f32_e32 v24, v24
	s_nop 0
	v_mul_f32_e32 v21, v21, v24
	v_mul_f32_e32 v22, v22, v24
	v_mul_f32_e32 v23, v23, v24
	s_waitcnt vmcnt(13)
	v_lshlrev_b32_e32 v25, 16, v116
	v_and_b32_e32 v26, 0xffff0000, v116
	v_lshlrev_b32_e32 v27, 16, v120
	v_and_b32_e32 v28, 0xffff0000, v120
	v_lshlrev_b32_e32 v29, 16, v124
	v_and_b32_e32 v30, 0xffff0000, v124
	v_mul_f32_e32 v31, v21, v25
	v_mul_f32_e32 v32, v22, v28
	v_fmac_f32_e32 v31, v22, v27
	v_fmac_f32_e32 v32, v21, v26
	v_fmac_f32_e32 v31, v23, v29
	v_fmac_f32_e32 v32, v23, v30
	v_cvt_pk_bf16_f32 v116, v31, v32
	v_lshlrev_b32_e32 v25, 16, v117
	v_and_b32_e32 v26, 0xffff0000, v117
	v_lshlrev_b32_e32 v27, 16, v121
	v_and_b32_e32 v28, 0xffff0000, v121
	v_lshlrev_b32_e32 v29, 16, v125
	v_and_b32_e32 v30, 0xffff0000, v125
	v_mul_f32_e32 v31, v21, v25
	v_mul_f32_e32 v32, v22, v28
	v_fmac_f32_e32 v31, v22, v27
	v_fmac_f32_e32 v32, v21, v26
	v_fmac_f32_e32 v31, v23, v29
	v_fmac_f32_e32 v32, v23, v30
	v_cvt_pk_bf16_f32 v117, v31, v32
	v_lshlrev_b32_e32 v25, 16, v118
	v_and_b32_e32 v26, 0xffff0000, v118
	v_lshlrev_b32_e32 v27, 16, v122
	v_and_b32_e32 v28, 0xffff0000, v122
	v_lshlrev_b32_e32 v29, 16, v126
	v_and_b32_e32 v30, 0xffff0000, v126
	v_mul_f32_e32 v31, v21, v25
	v_mul_f32_e32 v32, v22, v28
	v_fmac_f32_e32 v31, v22, v27
	v_fmac_f32_e32 v32, v21, v26
	v_fmac_f32_e32 v31, v23, v29
	v_fmac_f32_e32 v32, v23, v30
	v_cvt_pk_bf16_f32 v118, v31, v32
	v_lshlrev_b32_e32 v25, 16, v119
	v_and_b32_e32 v26, 0xffff0000, v119
	v_lshlrev_b32_e32 v27, 16, v123
	v_and_b32_e32 v28, 0xffff0000, v123
	v_lshlrev_b32_e32 v29, 16, v127
	v_and_b32_e32 v30, 0xffff0000, v127
	v_mul_f32_e32 v31, v21, v25
	v_mul_f32_e32 v32, v22, v28
	v_fmac_f32_e32 v31, v22, v27
	v_fmac_f32_e32 v32, v21, v26
	v_fmac_f32_e32 v31, v23, v29
	v_fmac_f32_e32 v32, v23, v30
	v_cvt_pk_bf16_f32 v119, v31, v32
	global_store_dwordx4 v14, v[116:119], s[8:9]
	s_add_u32 s8, s8, 0x200000
	s_addc_u32 s9, s9, 0
	v_max3_f32 v20, v179, v180, v181
	v_sub_f32_e32 v21, v179, v20
	v_sub_f32_e32 v22, v180, v20
	v_sub_f32_e32 v23, v181, v20
	v_mul_f32_e32 v21, 0x3fb8aa3b, v21
	v_mul_f32_e32 v22, 0x3fb8aa3b, v22
	v_mul_f32_e32 v23, 0x3fb8aa3b, v23
	v_exp_f32_e32 v21, v21
	v_exp_f32_e32 v22, v22
	v_exp_f32_e32 v23, v23
	s_nop 0
	v_add_f32_e32 v24, v21, v22
	v_add_f32_e32 v24, v23, v24
	v_rcp_f32_e32 v24, v24
	s_nop 0
	v_mul_f32_e32 v21, v21, v24
	v_mul_f32_e32 v22, v22, v24
	v_mul_f32_e32 v23, v23, v24
	s_waitcnt vmcnt(11)
; __device__ __forceinline__ unsigned cvt_pk_bf16(float lo, float hi) { f32x2_t v = {lo, hi}; bf2_t r = __builtin_convertvector(v, bf2_t); return __builtin_bit_cast(unsigned, r); }
; __device__ __forceinline__ float bflo(unsigned u) { return __uint_as_float(u << 16); }
; __device__ __forceinline__ float bfhi(unsigned u) { return __uint_as_float(u & 0xffff0000u); }
; __device__ __forceinline__ void attn_combine(const Ctx& C) {
;     ...
;     for (int idx = C.bid * NTHR + C.tid; idx < M_TOK * 32; idx += C.G * NTHR) {
;         const int tok = idx >> 5, j = (idx >> 3) & 3, c8 = idx & 7;
;         const float l0 = lse[((size_t)0 * M_TOK + tok) * 4 + j], l1 = lse[((size_t)1 * M_TOK + tok) * 4 + j], l2 = lse[((size_t)2 * M_TOK + tok) * 4 + j];
;         const float mx = fmaxf(l0, fmaxf(l1, l2)); float w0 = __expf(l0 - mx), w1 = __expf(l1 - mx), w2 = __expf(l2 - mx); const float inv = 1.0f / (w0 + w1 + w2); w0 *= inv; w1 *= inv; w2 *= inv;
;         const bf16_t* row = pd + (size_t)tok * 2304 + j * 64 + c8 * 8;
;         const u32x4 o0 = *(const u32x4*)row, o1 = *(const u32x4*)(row + 256), o2 = *(const u32x4*)(row + 512);
;         u32x4 o;
;         o.x = cvt_pk_bf16(w0 * bflo(o0.x) + w1 * bflo(o1.x) + w2 * bflo(o2.x), w0 * bfhi(o0.x) + w1 * bfhi(o1.x) + w2 * bfhi(o2.x));
;         o.y = cvt_pk_bf16(w0 * bflo(o0.y) + w1 * bflo(o1.y) + w2 * bflo(o2.y), w0 * bfhi(o0.y) + w1 * bfhi(o1.y) + w2 * bfhi(o2.y));
;         o.z = cvt_pk_bf16(w0 * bflo(o0.z) + w1 * bflo(o1.z) + w2 * bflo(o2.z), w0 * bfhi(o0.z) + w1 * bfhi(o1.z) + w2 * bfhi(o2.z));
;         o.w = cvt_pk_bf16(w0 * bflo(o0.w) + w1 * bflo(o1.w) + w2 * bflo(o2.w), w0 * bfhi(o0.w) + w1 * bfhi(o1.w) + w2 * bfhi(o2.w));
;         *(u32x4*)(yd + (size_t)tok * 256 + j * 64 + c8 * 8) = o;
	v_lshlrev_b32_e32 v25, 16, v128
	v_and_b32_e32 v26, 0xffff0000, v128
	v_lshlrev_b32_e32 v27, 16, v132
	v_and_b32_e32 v28, 0xffff0000, v132
	v_lshlrev_b32_e32 v29, 16, v136
	v_and_b32_e32 v30, 0xffff0000, v136
	v_mul_f32_e32 v31, v21, v25
	v_mul_f32_e32 v32, v22, v28
	v_fmac_f32_e32 v31, v22, v27
	v_fmac_f32_e32 v32, v21, v26
	v_fmac_f32_e32 v31, v23, v29
	v_fmac_f32_e32 v32, v23, v30
	v_cvt_pk_bf16_f32 v128, v31, v32
	v_lshlrev_b32_e32 v25, 16, v129
	v_and_b32_e32 v26, 0xffff0000, v129
	v_lshlrev_b32_e32 v27, 16, v133
	v_and_b32_e32 v28, 0xffff0000, v133
	v_lshlrev_b32_e32 v29, 16, v137
	v_and_b32_e32 v30, 0xffff0000, v137
	v_mul_f32_e32 v31, v21, v25
	v_mul_f32_e32 v32, v22, v28
	v_fmac_f32_e32 v31, v22, v27
	v_fmac_f32_e32 v32, v21, v26
	v_fmac_f32_e32 v31, v23, v29
	v_fmac_f32_e32 v32, v23, v30
	v_cvt_pk_bf16_f32 v129, v31, v32
	v_lshlrev_b32_e32 v25, 16, v130
	v_and_b32_e32 v26, 0xffff0000, v130
	v_lshlrev_b32_e32 v27, 16, v134
	v_and_b32_e32 v28, 0xffff0000, v134
	v_lshlrev_b32_e32 v29, 16, v138
	v_and_b32_e32 v30, 0xffff0000, v138
	v_mul_f32_e32 v31, v21, v25
	v_mul_f32_e32 v32, v22, v28
	v_fmac_f32_e32 v31, v22, v27
	v_fmac_f32_e32 v32, v21, v26
	v_fmac_f32_e32 v31, v23, v29
	v_fmac_f32_e32 v32, v23, v30
	v_cvt_pk_bf16_f32 v130, v31, v32
	v_lshlrev_b32_e32 v25, 16, v131
	v_and_b32_e32 v26, 0xffff0000, v131
	v_lshlrev_b32_e32 v27, 16, v135
	v_and_b32_e32 v28, 0xffff0000, v135
	v_lshlrev_b32_e32 v29, 16, v139
	v_and_b32_e32 v30, 0xffff0000, v139
	v_mul_f32_e32 v31, v21, v25
	v_mul_f32_e32 v32, v22, v28
	v_fmac_f32_e32 v31, v22, v27
	v_fmac_f32_e32 v32, v21, v26
	v_fmac_f32_e32 v31, v23, v29
	v_fmac_f32_e32 v32, v23, v30
	v_cvt_pk_bf16_f32 v131, v31, v32
	global_store_dwordx4 v14, v[128:131], s[8:9]
	s_add_u32 s8, s8, 0x200000
	s_addc_u32 s9, s9, 0
	v_max3_f32 v20, v188, v189, v190
	v_sub_f32_e32 v21, v188, v20
	v_sub_f32_e32 v22, v189, v20
	v_sub_f32_e32 v23, v190, v20
	v_mul_f32_e32 v21, 0x3fb8aa3b, v21
	v_mul_f32_e32 v22, 0x3fb8aa3b, v22
	v_mul_f32_e32 v23, 0x3fb8aa3b, v23
	v_exp_f32_e32 v21, v21
	v_exp_f32_e32 v22, v22
	v_exp_f32_e32 v23, v23
	s_nop 0
	v_add_f32_e32 v24, v21, v22
	v_add_f32_e32 v24, v23, v24
	v_rcp_f32_e32 v24, v24
	s_nop 0
	v_mul_f32_e32 v21, v21, v24
	v_mul_f32_e32 v22, v22, v24
	v_mul_f32_e32 v23, v23, v24
	s_waitcnt vmcnt(9)
	v_lshlrev_b32_e32 v25, 16, v140
	v_and_b32_e32 v26, 0xffff0000, v140
	v_lshlrev_b32_e32 v27, 16, v144
	v_and_b32_e32 v28, 0xffff0000, v144
	v_lshlrev_b32_e32 v29, 16, v148
	v_and_b32_e32 v30, 0xffff0000, v148
	v_mul_f32_e32 v31, v21, v25
	v_mul_f32_e32 v32, v22, v28
	v_fmac_f32_e32 v31, v22, v27
	v_fmac_f32_e32 v32, v21, v26
	v_fmac_f32_e32 v31, v23, v29
	v_fmac_f32_e32 v32, v23, v30
	v_cvt_pk_bf16_f32 v140, v31, v32
	v_lshlrev_b32_e32 v25, 16, v141
	v_and_b32_e32 v26, 0xffff0000, v141
	v_lshlrev_b32_e32 v27, 16, v145
	v_and_b32_e32 v28, 0xffff0000, v145
	v_lshlrev_b32_e32 v29, 16, v149
	v_and_b32_e32 v30, 0xffff0000, v149
	v_mul_f32_e32 v31, v21, v25
	v_mul_f32_e32 v32, v22, v28
	v_fmac_f32_e32 v31, v22, v27
	v_fmac_f32_e32 v32, v21, v26
	v_fmac_f32_e32 v31, v23, v29
	v_fmac_f32_e32 v32, v23, v30
	v_cvt_pk_bf16_f32 v141, v31, v32
	v_lshlrev_b32_e32 v25, 16, v142
	v_and_b32_e32 v26, 0xffff0000, v142
	v_lshlrev_b32_e32 v27, 16, v146
	v_and_b32_e32 v28, 0xffff0000, v146
	v_lshlrev_b32_e32 v29, 16, v150
	v_and_b32_e32 v30, 0xffff0000, v150
	v_mul_f32_e32 v31, v21, v25
	v_mul_f32_e32 v32, v22, v28
	v_fmac_f32_e32 v31, v22, v27
	v_fmac_f32_e32 v32, v21, v26
	v_fmac_f32_e32 v31, v23, v29
	v_fmac_f32_e32 v32, v23, v30
	v_cvt_pk_bf16_f32 v142, v31, v32
	v_lshlrev_b32_e32 v25, 16, v143
	v_and_b32_e32 v26, 0xffff0000, v143
	v_lshlrev_b32_e32 v27, 16, v147
	v_and_b32_e32 v28, 0xffff0000, v147
	v_lshlrev_b32_e32 v29, 16, v151
	v_and_b32_e32 v30, 0xffff0000, v151
	v_mul_f32_e32 v31, v21, v25
	v_mul_f32_e32 v32, v22, v28
	v_fmac_f32_e32 v31, v22, v27
	v_fmac_f32_e32 v32, v21, v26
	v_fmac_f32_e32 v31, v23, v29
	v_fmac_f32_e32 v32, v23, v30
	v_cvt_pk_bf16_f32 v143, v31, v32
	global_store_dwordx4 v14, v[140:143], s[8:9]
	s_add_u32 s8, s8, 0x200000
	s_addc_u32 s9, s9, 0
	v_max3_f32 v20, v191, v192, v193
	v_sub_f32_e32 v21, v191, v20
	v_sub_f32_e32 v22, v192, v20
	v_sub_f32_e32 v23, v193, v20
	v_mul_f32_e32 v21, 0x3fb8aa3b, v21
	v_mul_f32_e32 v22, 0x3fb8aa3b, v22
	v_mul_f32_e32 v23, 0x3fb8aa3b, v23
	v_exp_f32_e32 v21, v21
	v_exp_f32_e32 v22, v22
	v_exp_f32_e32 v23, v23
	s_nop 0
	v_add_f32_e32 v24, v21, v22
	v_add_f32_e32 v24, v23, v24
	v_rcp_f32_e32 v24, v24
	s_nop 0
	v_mul_f32_e32 v21, v21, v24
	v_mul_f32_e32 v22, v22, v24
	v_mul_f32_e32 v23, v23, v24
	s_waitcnt vmcnt(7)
	v_lshlrev_b32_e32 v25, 16, v152
	v_and_b32_e32 v26, 0xffff0000, v152
	v_lshlrev_b32_e32 v27, 16, v156
	v_and_b32_e32 v28, 0xffff0000, v156
	v_lshlrev_b32_e32 v29, 16, v160
	v_and_b32_e32 v30, 0xffff0000, v160
	v_mul_f32_e32 v31, v21, v25
	v_mul_f32_e32 v32, v22, v28
	v_fmac_f32_e32 v31, v22, v27
	v_fmac_f32_e32 v32, v21, v26
	v_fmac_f32_e32 v31, v23, v29
	v_fmac_f32_e32 v32, v23, v30
	v_cvt_pk_bf16_f32 v152, v31, v32
	v_lshlrev_b32_e32 v25, 16, v153
	v_and_b32_e32 v26, 0xffff0000, v153
	v_lshlrev_b32_e32 v27, 16, v157
	v_and_b32_e32 v28, 0xffff0000, v157
	v_lshlrev_b32_e32 v29, 16, v161
	v_and_b32_e32 v30, 0xffff0000, v161
	v_mul_f32_e32 v31, v21, v25
	v_mul_f32_e32 v32, v22, v28
	v_fmac_f32_e32 v31, v22, v27
	v_fmac_f32_e32 v32, v21, v26
	v_fmac_f32_e32 v31, v23, v29
	v_fmac_f32_e32 v32, v23, v30
	v_cvt_pk_bf16_f32 v153, v31, v32
	v_lshlrev_b32_e32 v25, 16, v154
	v_and_b32_e32 v26, 0xffff0000, v154
	v_lshlrev_b32_e32 v27, 16, v158
	v_and_b32_e32 v28, 0xffff0000, v158
	v_lshlrev_b32_e32 v29, 16, v162
	v_and_b32_e32 v30, 0xffff0000, v162
	v_mul_f32_e32 v31, v21, v25
	v_mul_f32_e32 v32, v22, v28
	v_fmac_f32_e32 v31, v22, v27
	v_fmac_f32_e32 v32, v21, v26
	v_fmac_f32_e32 v31, v23, v29
	v_fmac_f32_e32 v32, v23, v30
	v_cvt_pk_bf16_f32 v154, v31, v32
	v_lshlrev_b32_e32 v25, 16, v155
	v_and_b32_e32 v26, 0xffff0000, v155
	v_lshlrev_b32_e32 v27, 16, v159
	v_and_b32_e32 v28, 0xffff0000, v159
	v_lshlrev_b32_e32 v29, 16, v163
	v_and_b32_e32 v30, 0xffff0000, v163
	v_mul_f32_e32 v31, v21, v25
	v_mul_f32_e32 v32, v22, v28
	v_fmac_f32_e32 v31, v22, v27
	v_fmac_f32_e32 v32, v21, v26
	v_fmac_f32_e32 v31, v23, v29
	v_fmac_f32_e32 v32, v23, v30
	v_cvt_pk_bf16_f32 v155, v31, v32
	global_store_dwordx4 v14, v[152:155], s[8:9]
	s_add_i32 s101, s101, 1
	s_sub_i32 s100, s100, 0x10000
	s_cmp_lg_u32 s101, 2
	s_cbranch_scc1 .Lmy_cmb_pass
.Lmy_cmb_done:
	s_mov_b64 s[10:11], exec
	s_mov_b32 s12, 0xfffff
	s_mov_b32 s13, 0
	s_mov_b64 s[0:1], exec
	s_branch .LBB0_754
